# v78 + four missing M0-to-DMA wait states restored (s_nop 0)
# speedup vs baseline: 1.0036x; 1.0036x over previous
.LBB0_837:
	s_ashr_i32 s15, s14, 31
	s_lshl_b64 s[78:79], s[14:15], 19
	s_add_u32 s84, s36, s78
	s_addc_u32 s85, s37, s79
	s_and_b64 s[4:5], s[4:5], exec
	s_cselect_b32 s15, s85, s91
	s_cselect_b32 s23, s84, s90
	s_add_u32 s34, s90, 0x100
	s_addc_u32 s75, s91, 0
	s_mov_b32 s78, -2
	s_waitcnt lgkmcnt(0)
	s_add_i32 s79, 0, 0x10000
	v_add_u32_e32 v142, s79, v212
	v_add_u32_e32 v189, 0x10000, v212
	ds_read_b128 v[130:133], v142
	ds_read_b128 v[134:137], v142 offset:1024
	ds_read_b128 v[138:141], v142 offset:2048
	ds_read_b128 v[142:145], v142 offset:3072
	s_add_u32 s4, s88, 0x100
	s_addc_u32 s5, s89, 0
	s_cmp_eq_u32 s78, 12
	s_cselect_b32 s93, s17, s5
	s_cselect_b32 s92, s16, s4
	s_cselect_b32 s91, s15, s75
	s_cselect_b32 s90, s23, s34
	v_lshl_add_u64 v[178:179], s[88:89], 0, v[196:197]
	s_add_i32 m0, s39, 0xc000
	ds_read_b128 v[146:149], v213
	ds_read_b128 v[150:153], v213 offset:1024
	ds_read_b128 v[154:157], v213 offset:2048
	ds_read_b128 v[158:161], v213 offset:3072
	ds_read_b128 v[162:165], v213 offset:4096
	ds_read_b128 v[166:169], v213 offset:5120
	ds_read_b128 v[170:173], v213 offset:6144
	ds_read_b128 v[174:177], v213 offset:7168
	global_load_lds_dwordx4 v[178:179], off
	s_add_i32 m0, s39, 0xe000
	v_lshl_add_u64 v[178:179], s[88:89], 0, v[198:199]
	global_load_lds_dwordx4 v[178:179], off
	s_waitcnt lgkmcnt(8)
	s_barrier
	s_waitcnt lgkmcnt(0)
	v_mfma_f32_16x16x32_bf16 v[126:129], v[130:133], v[146:149], 0
	v_mfma_f32_16x16x32_bf16 v[122:125], v[138:141], v[146:149], 0
	v_mfma_f32_16x16x32_bf16 v[110:113], v[130:133], v[154:157], 0
	v_mfma_f32_16x16x32_bf16 v[106:109], v[138:141], v[154:157], 0
	v_mfma_f32_16x16x32_bf16 v[94:97], v[130:133], v[162:165], 0
	v_mfma_f32_16x16x32_bf16 v[90:93], v[138:141], v[162:165], 0
	v_mfma_f32_16x16x32_bf16 v[78:81], v[130:133], v[170:173], 0
	v_mfma_f32_16x16x32_bf16 v[74:77], v[138:141], v[170:173], 0
	v_mfma_f32_16x16x32_bf16 v[126:129], v[134:137], v[150:153], v[126:129]
	v_mfma_f32_16x16x32_bf16 v[122:125], v[142:145], v[150:153], v[122:125]
	v_mfma_f32_16x16x32_bf16 v[110:113], v[134:137], v[158:161], v[110:113]
	v_mfma_f32_16x16x32_bf16 v[106:109], v[142:145], v[158:161], v[106:109]
	v_mfma_f32_16x16x32_bf16 v[94:97], v[134:137], v[166:169], v[94:97]
	v_mfma_f32_16x16x32_bf16 v[90:93], v[142:145], v[166:169], v[90:93]
	v_mfma_f32_16x16x32_bf16 v[78:81], v[134:137], v[174:177], v[78:81]
	v_mfma_f32_16x16x32_bf16 v[74:77], v[142:145], v[174:177], v[74:77]
	s_barrier
	ds_read_b128 v[178:181], v189 offset:16384
	ds_read_b128 v[182:185], v189 offset:17408
	ds_read_b128 v[200:203], v189 offset:18432
	ds_read_b128 v[204:207], v189 offset:19456
	s_add_i32 m0, s38, 0x10000
	s_nop 0
	global_load_lds_dwordx4 v0, s[90:91]
	s_add_i32 m0, s38, 0x12000
	s_nop 0
	global_load_lds_dwordx4 v194, s[90:91]
	s_barrier
	s_waitcnt lgkmcnt(0)
	v_mfma_f32_16x16x32_bf16 v[118:121], v[178:181], v[146:149], 0
	v_mfma_f32_16x16x32_bf16 v[114:117], v[200:203], v[146:149], 0
	v_mfma_f32_16x16x32_bf16 v[102:105], v[178:181], v[154:157], 0
	v_mfma_f32_16x16x32_bf16 v[98:101], v[200:203], v[154:157], 0
	v_mfma_f32_16x16x32_bf16 v[86:89], v[178:181], v[162:165], 0
	v_mfma_f32_16x16x32_bf16 v[82:85], v[200:203], v[162:165], 0
	v_mfma_f32_16x16x32_bf16 v[70:73], v[178:181], v[170:173], 0
	v_mfma_f32_16x16x32_bf16 v[66:69], v[200:203], v[170:173], 0
	v_mfma_f32_16x16x32_bf16 v[118:121], v[182:185], v[150:153], v[118:121]
	v_mfma_f32_16x16x32_bf16 v[114:117], v[204:207], v[150:153], v[114:117]
	v_mfma_f32_16x16x32_bf16 v[102:105], v[182:185], v[158:161], v[102:105]
	v_mfma_f32_16x16x32_bf16 v[98:101], v[204:207], v[158:161], v[98:101]
	v_mfma_f32_16x16x32_bf16 v[86:89], v[182:185], v[166:169], v[86:89]
	v_mfma_f32_16x16x32_bf16 v[82:85], v[204:207], v[166:169], v[82:85]
	v_mfma_f32_16x16x32_bf16 v[70:73], v[182:185], v[174:177], v[70:73]
	v_mfma_f32_16x16x32_bf16 v[66:69], v[204:207], v[174:177], v[66:69]
	s_mov_b32 m0, s39
	s_barrier
	ds_read_b128 v[146:149], v213 offset:16384
	ds_read_b128 v[150:153], v213 offset:17408
	ds_read_b128 v[154:157], v213 offset:18432
	ds_read_b128 v[158:161], v213 offset:19456
	ds_read_b128 v[162:165], v213 offset:20480
	ds_read_b128 v[166:169], v213 offset:21504
	ds_read_b128 v[170:173], v213 offset:22528
	ds_read_b128 v[174:177], v213 offset:23552
	global_load_lds_dwordx4 v190, s[92:93]
	s_mov_b32 m0, s42
	s_nop 0
	global_load_lds_dwordx4 v192, s[92:93]
	s_waitcnt vmcnt(10)
	s_barrier
	s_waitcnt lgkmcnt(0)
	v_mfma_f32_16x16x32_bf16 v[62:65], v[130:133], v[146:149], 0
	v_mfma_f32_16x16x32_bf16 v[58:61], v[138:141], v[146:149], 0
	v_mfma_f32_16x16x32_bf16 v[46:49], v[130:133], v[154:157], 0
	v_mfma_f32_16x16x32_bf16 v[42:45], v[138:141], v[154:157], 0
	v_mfma_f32_16x16x32_bf16 v[30:33], v[130:133], v[162:165], 0
	v_mfma_f32_16x16x32_bf16 v[26:29], v[138:141], v[162:165], 0
	v_mfma_f32_16x16x32_bf16 v[14:17], v[130:133], v[170:173], 0
	v_mfma_f32_16x16x32_bf16 v[10:13], v[138:141], v[170:173], 0
	v_mfma_f32_16x16x32_bf16 v[62:65], v[134:137], v[150:153], v[62:65]
	v_mfma_f32_16x16x32_bf16 v[58:61], v[142:145], v[150:153], v[58:61]
	v_mfma_f32_16x16x32_bf16 v[46:49], v[134:137], v[158:161], v[46:49]
	v_mfma_f32_16x16x32_bf16 v[42:45], v[142:145], v[158:161], v[42:45]
	v_mfma_f32_16x16x32_bf16 v[30:33], v[134:137], v[166:169], v[30:33]
	v_mfma_f32_16x16x32_bf16 v[26:29], v[142:145], v[166:169], v[26:29]
	v_mfma_f32_16x16x32_bf16 v[14:17], v[134:137], v[174:177], v[14:17]
	v_mfma_f32_16x16x32_bf16 v[10:13], v[142:145], v[174:177], v[10:13]
	s_barrier
	s_add_u32 s88, s90, 0x40000
	s_addc_u32 s89, s91, 0
	s_add_i32 m0, s38, 0x14000
	s_nop 0
	global_load_lds_dwordx4 v0, s[88:89]
	s_add_i32 m0, s38, 0x16000
	s_nop 0
	global_load_lds_dwordx4 v194, s[88:89]
	s_add_i32 s79, 0, 0x18000
	v_add_u32_e32 v142, s79, v212
	ds_read_b128 v[130:133], v142
	ds_read_b128 v[134:137], v142 offset:1024
	ds_read_b128 v[138:141], v142 offset:2048
	ds_read_b128 v[142:145], v142 offset:3072
	s_waitcnt vmcnt(6)
	s_barrier
	v_mfma_f32_16x16x32_bf16 v[54:57], v[178:181], v[146:149], 0
	v_mfma_f32_16x16x32_bf16 v[50:53], v[200:203], v[146:149], 0
	v_mfma_f32_16x16x32_bf16 v[38:41], v[178:181], v[154:157], 0
	v_mfma_f32_16x16x32_bf16 v[34:37], v[200:203], v[154:157], 0
	v_mfma_f32_16x16x32_bf16 v[22:25], v[178:181], v[162:165], 0
	v_mfma_f32_16x16x32_bf16 v[18:21], v[200:203], v[162:165], 0
	v_mfma_f32_16x16x32_bf16 v[6:9], v[178:181], v[170:173], 0
	v_mfma_f32_16x16x32_bf16 v[2:5], v[200:203], v[170:173], 0
	v_mfma_f32_16x16x32_bf16 v[54:57], v[182:185], v[150:153], v[54:57]
	v_mfma_f32_16x16x32_bf16 v[50:53], v[204:207], v[150:153], v[50:53]
	v_mfma_f32_16x16x32_bf16 v[38:41], v[182:185], v[158:161], v[38:41]
	v_mfma_f32_16x16x32_bf16 v[34:37], v[204:207], v[158:161], v[34:37]
	v_mfma_f32_16x16x32_bf16 v[22:25], v[182:185], v[166:169], v[22:25]
	v_mfma_f32_16x16x32_bf16 v[18:21], v[204:207], v[166:169], v[18:21]
	v_mfma_f32_16x16x32_bf16 v[6:9], v[182:185], v[174:177], v[6:9]
	v_mfma_f32_16x16x32_bf16 v[2:5], v[204:207], v[174:177], v[2:5]
	s_barrier
	s_add_u32 s88, s92, 0xc0000
	s_addc_u32 s89, s93, 0
	s_mov_b32 m0, s43
	ds_read_b128 v[146:149], v213 offset:32768
	ds_read_b128 v[150:153], v213 offset:33792
	ds_read_b128 v[154:157], v213 offset:34816
	ds_read_b128 v[158:161], v213 offset:35840
	ds_read_b128 v[162:165], v213 offset:36864
	ds_read_b128 v[166:169], v213 offset:37888
	ds_read_b128 v[170:173], v213 offset:38912
	ds_read_b128 v[174:177], v213 offset:39936
	global_load_lds_dwordx4 v190, s[88:89]
	s_mov_b32 m0, s44
	s_nop 0
	global_load_lds_dwordx4 v192, s[88:89]
	s_waitcnt lgkmcnt(8)
	s_barrier
	s_waitcnt lgkmcnt(0)
	v_mfma_f32_16x16x32_bf16 v[126:129], v[130:133], v[146:149], v[126:129]
	v_mfma_f32_16x16x32_bf16 v[122:125], v[138:141], v[146:149], v[122:125]
	v_mfma_f32_16x16x32_bf16 v[110:113], v[130:133], v[154:157], v[110:113]
	v_mfma_f32_16x16x32_bf16 v[106:109], v[138:141], v[154:157], v[106:109]
	v_mfma_f32_16x16x32_bf16 v[94:97], v[130:133], v[162:165], v[94:97]
	v_mfma_f32_16x16x32_bf16 v[90:93], v[138:141], v[162:165], v[90:93]
	v_mfma_f32_16x16x32_bf16 v[78:81], v[130:133], v[170:173], v[78:81]
	v_mfma_f32_16x16x32_bf16 v[74:77], v[138:141], v[170:173], v[74:77]
	v_mfma_f32_16x16x32_bf16 v[126:129], v[134:137], v[150:153], v[126:129]
	v_mfma_f32_16x16x32_bf16 v[122:125], v[142:145], v[150:153], v[122:125]
	v_mfma_f32_16x16x32_bf16 v[110:113], v[134:137], v[158:161], v[110:113]
	v_mfma_f32_16x16x32_bf16 v[106:109], v[142:145], v[158:161], v[106:109]
	v_mfma_f32_16x16x32_bf16 v[94:97], v[134:137], v[166:169], v[94:97]
	v_mfma_f32_16x16x32_bf16 v[90:93], v[142:145], v[166:169], v[90:93]
	v_mfma_f32_16x16x32_bf16 v[78:81], v[134:137], v[174:177], v[78:81]
	v_mfma_f32_16x16x32_bf16 v[74:77], v[142:145], v[174:177], v[74:77]
	s_barrier
	s_add_i32 s87, 0, 0x1c000
	v_add_u32_e32 v204, s87, v212
	s_add_i32 m0, s38, 0x18000
	ds_read_b128 v[178:181], v204
	ds_read_b128 v[182:185], v204 offset:1024
	ds_read_b128 v[200:203], v204 offset:2048
	ds_read_b128 v[204:207], v204 offset:3072
	s_add_u32 s98, s90, s40
	s_addc_u32 s99, s91, s41
	global_load_lds_dwordx4 v0, s[98:99]
	s_add_i32 m0, s38, 0x1a000
	s_nop 0
	global_load_lds_dwordx4 v194, s[98:99]
	s_barrier
	s_waitcnt lgkmcnt(0)
	v_mfma_f32_16x16x32_bf16 v[118:121], v[178:181], v[146:149], v[118:121]
	v_mfma_f32_16x16x32_bf16 v[114:117], v[200:203], v[146:149], v[114:117]
	v_mfma_f32_16x16x32_bf16 v[102:105], v[178:181], v[154:157], v[102:105]
	v_mfma_f32_16x16x32_bf16 v[98:101], v[200:203], v[154:157], v[98:101]
	v_mfma_f32_16x16x32_bf16 v[86:89], v[178:181], v[162:165], v[86:89]
	v_mfma_f32_16x16x32_bf16 v[82:85], v[200:203], v[162:165], v[82:85]
	v_mfma_f32_16x16x32_bf16 v[70:73], v[178:181], v[170:173], v[70:73]
	v_mfma_f32_16x16x32_bf16 v[66:69], v[200:203], v[170:173], v[66:69]
	v_mfma_f32_16x16x32_bf16 v[118:121], v[182:185], v[150:153], v[118:121]
	v_mfma_f32_16x16x32_bf16 v[114:117], v[204:207], v[150:153], v[114:117]
	v_mfma_f32_16x16x32_bf16 v[102:105], v[182:185], v[158:161], v[102:105]
	v_mfma_f32_16x16x32_bf16 v[98:101], v[204:207], v[158:161], v[98:101]
	v_mfma_f32_16x16x32_bf16 v[86:89], v[182:185], v[166:169], v[86:89]
	v_mfma_f32_16x16x32_bf16 v[82:85], v[204:207], v[166:169], v[82:85]
	v_mfma_f32_16x16x32_bf16 v[70:73], v[182:185], v[174:177], v[70:73]
	v_mfma_f32_16x16x32_bf16 v[66:69], v[204:207], v[174:177], v[66:69]
	s_mov_b32 m0, s60
	s_barrier
	ds_read_b128 v[146:149], v213 offset:49152
	ds_read_b128 v[150:153], v213 offset:50176
	ds_read_b128 v[154:157], v213 offset:51200
	ds_read_b128 v[158:161], v213 offset:52224
	ds_read_b128 v[162:165], v213 offset:53248
	ds_read_b128 v[166:169], v213 offset:54272
	ds_read_b128 v[170:173], v213 offset:55296
	ds_read_b128 v[174:177], v213 offset:56320
	s_add_u32 s98, s92, s40
	s_addc_u32 s99, s93, s41
	global_load_lds_dwordx4 v190, s[98:99]
	s_mov_b32 m0, s61
	s_nop 0
	global_load_lds_dwordx4 v192, s[98:99]
	s_waitcnt vmcnt(10)
	s_barrier
	s_waitcnt lgkmcnt(0)
	v_mfma_f32_16x16x32_bf16 v[62:65], v[130:133], v[146:149], v[62:65]
	v_mfma_f32_16x16x32_bf16 v[58:61], v[138:141], v[146:149], v[58:61]
	v_mfma_f32_16x16x32_bf16 v[46:49], v[130:133], v[154:157], v[46:49]
	v_mfma_f32_16x16x32_bf16 v[42:45], v[138:141], v[154:157], v[42:45]
	v_mfma_f32_16x16x32_bf16 v[30:33], v[130:133], v[162:165], v[30:33]
	v_mfma_f32_16x16x32_bf16 v[26:29], v[138:141], v[162:165], v[26:29]
	v_mfma_f32_16x16x32_bf16 v[14:17], v[130:133], v[170:173], v[14:17]
	v_mfma_f32_16x16x32_bf16 v[10:13], v[138:141], v[170:173], v[10:13]
	v_mfma_f32_16x16x32_bf16 v[62:65], v[134:137], v[150:153], v[62:65]
	v_mfma_f32_16x16x32_bf16 v[58:61], v[142:145], v[150:153], v[58:61]
	v_mfma_f32_16x16x32_bf16 v[46:49], v[134:137], v[158:161], v[46:49]
	v_mfma_f32_16x16x32_bf16 v[42:45], v[142:145], v[158:161], v[42:45]
	v_mfma_f32_16x16x32_bf16 v[30:33], v[134:137], v[166:169], v[30:33]
	v_mfma_f32_16x16x32_bf16 v[26:29], v[142:145], v[166:169], v[26:29]
	v_mfma_f32_16x16x32_bf16 v[14:17], v[134:137], v[174:177], v[14:17]
	v_mfma_f32_16x16x32_bf16 v[10:13], v[142:145], v[174:177], v[10:13]
	s_barrier
	s_add_u32 s88, s90, 0x40080
	s_addc_u32 s89, s91, 0
	s_add_i32 m0, s38, 0x1c000
	s_nop 0
	global_load_lds_dwordx4 v0, s[88:89]
	s_add_i32 m0, s38, 0x1e000
	s_nop 0
	global_load_lds_dwordx4 v194, s[88:89]
	ds_read_b128 v[130:133], v189
	ds_read_b128 v[134:137], v189 offset:1024
	ds_read_b128 v[138:141], v189 offset:2048
	ds_read_b128 v[142:145], v189 offset:3072
	s_waitcnt vmcnt(6)
	s_barrier
	v_mfma_f32_16x16x32_bf16 v[54:57], v[178:181], v[146:149], v[54:57]
	v_mfma_f32_16x16x32_bf16 v[50:53], v[200:203], v[146:149], v[50:53]
	v_mfma_f32_16x16x32_bf16 v[38:41], v[178:181], v[154:157], v[38:41]
	v_mfma_f32_16x16x32_bf16 v[34:37], v[200:203], v[154:157], v[34:37]
	v_mfma_f32_16x16x32_bf16 v[22:25], v[178:181], v[162:165], v[22:25]
	v_mfma_f32_16x16x32_bf16 v[18:21], v[200:203], v[162:165], v[18:21]
	v_mfma_f32_16x16x32_bf16 v[6:9], v[178:181], v[170:173], v[6:9]
	v_mfma_f32_16x16x32_bf16 v[2:5], v[200:203], v[170:173], v[2:5]
	v_mfma_f32_16x16x32_bf16 v[54:57], v[182:185], v[150:153], v[54:57]
	v_mfma_f32_16x16x32_bf16 v[50:53], v[204:207], v[150:153], v[50:53]
	v_mfma_f32_16x16x32_bf16 v[38:41], v[182:185], v[158:161], v[38:41]
	v_mfma_f32_16x16x32_bf16 v[34:37], v[204:207], v[158:161], v[34:37]
	v_mfma_f32_16x16x32_bf16 v[22:25], v[182:185], v[166:169], v[22:25]
	v_mfma_f32_16x16x32_bf16 v[18:21], v[204:207], v[166:169], v[18:21]
	v_mfma_f32_16x16x32_bf16 v[6:9], v[182:185], v[174:177], v[6:9]
	v_mfma_f32_16x16x32_bf16 v[2:5], v[204:207], v[174:177], v[2:5]
	s_add_i32 s78, s78, 2
	s_add_u32 s34, s34, 0x100
	s_addc_u32 s75, s75, 0
	s_mov_b64 s[88:89], s[4:5]
	s_add_u32 s4, s88, 0x100
	s_addc_u32 s5, s89, 0
	s_cmp_eq_u32 s78, 12
	s_cselect_b32 s93, s17, s5
	s_cselect_b32 s92, s16, s4
	s_cselect_b32 s91, s15, s75
	s_cselect_b32 s90, s23, s34
	s_cmp_gt_u32 s78, 13
	s_barrier
.LBB0_838:
	v_lshl_add_u64 v[178:179], s[88:89], 0, v[196:197]
	s_add_i32 m0, s39, 0xc000
	ds_read_b128 v[146:149], v213
	ds_read_b128 v[150:153], v213 offset:1024
	ds_read_b128 v[154:157], v213 offset:2048
	ds_read_b128 v[158:161], v213 offset:3072
	ds_read_b128 v[162:165], v213 offset:4096
	ds_read_b128 v[166:169], v213 offset:5120
	ds_read_b128 v[170:173], v213 offset:6144
	ds_read_b128 v[174:177], v213 offset:7168
	global_load_lds_dwordx4 v[178:179], off
	s_add_i32 m0, s39, 0xe000
	v_lshl_add_u64 v[178:179], s[88:89], 0, v[198:199]
	global_load_lds_dwordx4 v[178:179], off
	s_waitcnt lgkmcnt(8)
	s_barrier
	s_waitcnt lgkmcnt(0)
	v_mfma_f32_16x16x32_bf16 v[126:129], v[130:133], v[146:149], v[126:129]
	v_mfma_f32_16x16x32_bf16 v[122:125], v[138:141], v[146:149], v[122:125]
	v_mfma_f32_16x16x32_bf16 v[110:113], v[130:133], v[154:157], v[110:113]
	v_mfma_f32_16x16x32_bf16 v[106:109], v[138:141], v[154:157], v[106:109]
	v_mfma_f32_16x16x32_bf16 v[94:97], v[130:133], v[162:165], v[94:97]
	v_mfma_f32_16x16x32_bf16 v[90:93], v[138:141], v[162:165], v[90:93]
	v_mfma_f32_16x16x32_bf16 v[78:81], v[130:133], v[170:173], v[78:81]
	v_mfma_f32_16x16x32_bf16 v[74:77], v[138:141], v[170:173], v[74:77]
	v_mfma_f32_16x16x32_bf16 v[126:129], v[134:137], v[150:153], v[126:129]
	v_mfma_f32_16x16x32_bf16 v[122:125], v[142:145], v[150:153], v[122:125]
	v_mfma_f32_16x16x32_bf16 v[110:113], v[134:137], v[158:161], v[110:113]
	v_mfma_f32_16x16x32_bf16 v[106:109], v[142:145], v[158:161], v[106:109]
	v_mfma_f32_16x16x32_bf16 v[94:97], v[134:137], v[166:169], v[94:97]
	v_mfma_f32_16x16x32_bf16 v[90:93], v[142:145], v[166:169], v[90:93]
	v_mfma_f32_16x16x32_bf16 v[78:81], v[134:137], v[174:177], v[78:81]
	v_mfma_f32_16x16x32_bf16 v[74:77], v[142:145], v[174:177], v[74:77]
	s_barrier
	ds_read_b128 v[178:181], v189 offset:16384
	ds_read_b128 v[182:185], v189 offset:17408
	ds_read_b128 v[200:203], v189 offset:18432
	ds_read_b128 v[204:207], v189 offset:19456
	s_add_i32 m0, s38, 0x10000
	s_nop 0
	global_load_lds_dwordx4 v0, s[90:91]
	s_add_i32 m0, s38, 0x12000
	s_nop 0
	global_load_lds_dwordx4 v194, s[90:91]
	s_barrier
	s_waitcnt lgkmcnt(0)
	v_mfma_f32_16x16x32_bf16 v[118:121], v[178:181], v[146:149], v[118:121]
	v_mfma_f32_16x16x32_bf16 v[114:117], v[200:203], v[146:149], v[114:117]
	v_mfma_f32_16x16x32_bf16 v[102:105], v[178:181], v[154:157], v[102:105]
	v_mfma_f32_16x16x32_bf16 v[98:101], v[200:203], v[154:157], v[98:101]
	v_mfma_f32_16x16x32_bf16 v[86:89], v[178:181], v[162:165], v[86:89]
	v_mfma_f32_16x16x32_bf16 v[82:85], v[200:203], v[162:165], v[82:85]
	v_mfma_f32_16x16x32_bf16 v[70:73], v[178:181], v[170:173], v[70:73]
	v_mfma_f32_16x16x32_bf16 v[66:69], v[200:203], v[170:173], v[66:69]
	v_mfma_f32_16x16x32_bf16 v[118:121], v[182:185], v[150:153], v[118:121]
	v_mfma_f32_16x16x32_bf16 v[114:117], v[204:207], v[150:153], v[114:117]
	v_mfma_f32_16x16x32_bf16 v[102:105], v[182:185], v[158:161], v[102:105]
	v_mfma_f32_16x16x32_bf16 v[98:101], v[204:207], v[158:161], v[98:101]
	v_mfma_f32_16x16x32_bf16 v[86:89], v[182:185], v[166:169], v[86:89]
	v_mfma_f32_16x16x32_bf16 v[82:85], v[204:207], v[166:169], v[82:85]
	v_mfma_f32_16x16x32_bf16 v[70:73], v[182:185], v[174:177], v[70:73]
	v_mfma_f32_16x16x32_bf16 v[66:69], v[204:207], v[174:177], v[66:69]
	s_mov_b32 m0, s39
	s_barrier
	ds_read_b128 v[146:149], v213 offset:16384
	ds_read_b128 v[150:153], v213 offset:17408
	ds_read_b128 v[154:157], v213 offset:18432
	ds_read_b128 v[158:161], v213 offset:19456
	ds_read_b128 v[162:165], v213 offset:20480
	ds_read_b128 v[166:169], v213 offset:21504
	ds_read_b128 v[170:173], v213 offset:22528
	ds_read_b128 v[174:177], v213 offset:23552
	global_load_lds_dwordx4 v190, s[92:93]
	s_mov_b32 m0, s42
	s_nop 0
	global_load_lds_dwordx4 v192, s[92:93]
	s_waitcnt vmcnt(10)
	s_barrier
	s_waitcnt lgkmcnt(0)
	v_mfma_f32_16x16x32_bf16 v[62:65], v[130:133], v[146:149], v[62:65]
	v_mfma_f32_16x16x32_bf16 v[58:61], v[138:141], v[146:149], v[58:61]
	v_mfma_f32_16x16x32_bf16 v[46:49], v[130:133], v[154:157], v[46:49]
	v_mfma_f32_16x16x32_bf16 v[42:45], v[138:141], v[154:157], v[42:45]
	v_mfma_f32_16x16x32_bf16 v[30:33], v[130:133], v[162:165], v[30:33]
	v_mfma_f32_16x16x32_bf16 v[26:29], v[138:141], v[162:165], v[26:29]
	v_mfma_f32_16x16x32_bf16 v[14:17], v[130:133], v[170:173], v[14:17]
	v_mfma_f32_16x16x32_bf16 v[10:13], v[138:141], v[170:173], v[10:13]
	v_mfma_f32_16x16x32_bf16 v[62:65], v[134:137], v[150:153], v[62:65]
	v_mfma_f32_16x16x32_bf16 v[58:61], v[142:145], v[150:153], v[58:61]
	v_mfma_f32_16x16x32_bf16 v[46:49], v[134:137], v[158:161], v[46:49]
	v_mfma_f32_16x16x32_bf16 v[42:45], v[142:145], v[158:161], v[42:45]
	v_mfma_f32_16x16x32_bf16 v[30:33], v[134:137], v[166:169], v[30:33]
	v_mfma_f32_16x16x32_bf16 v[26:29], v[142:145], v[166:169], v[26:29]
	v_mfma_f32_16x16x32_bf16 v[14:17], v[134:137], v[174:177], v[14:17]
	v_mfma_f32_16x16x32_bf16 v[10:13], v[142:145], v[174:177], v[10:13]
	s_barrier
	s_add_u32 s88, s90, 0x40000
	s_addc_u32 s89, s91, 0
	s_add_i32 m0, s38, 0x14000
	s_nop 0
	global_load_lds_dwordx4 v0, s[88:89]
	s_add_i32 m0, s38, 0x16000
	s_nop 0
	global_load_lds_dwordx4 v194, s[88:89]
	s_add_i32 s79, 0, 0x18000
	v_add_u32_e32 v142, s79, v212
	ds_read_b128 v[130:133], v142
	ds_read_b128 v[134:137], v142 offset:1024
	ds_read_b128 v[138:141], v142 offset:2048
	ds_read_b128 v[142:145], v142 offset:3072
	s_waitcnt vmcnt(6)
	s_barrier
	v_mfma_f32_16x16x32_bf16 v[54:57], v[178:181], v[146:149], v[54:57]
	v_mfma_f32_16x16x32_bf16 v[50:53], v[200:203], v[146:149], v[50:53]
	v_mfma_f32_16x16x32_bf16 v[38:41], v[178:181], v[154:157], v[38:41]
	v_mfma_f32_16x16x32_bf16 v[34:37], v[200:203], v[154:157], v[34:37]
	v_mfma_f32_16x16x32_bf16 v[22:25], v[178:181], v[162:165], v[22:25]
	v_mfma_f32_16x16x32_bf16 v[18:21], v[200:203], v[162:165], v[18:21]
	v_mfma_f32_16x16x32_bf16 v[6:9], v[178:181], v[170:173], v[6:9]
	v_mfma_f32_16x16x32_bf16 v[2:5], v[200:203], v[170:173], v[2:5]
	v_mfma_f32_16x16x32_bf16 v[54:57], v[182:185], v[150:153], v[54:57]
	v_mfma_f32_16x16x32_bf16 v[50:53], v[204:207], v[150:153], v[50:53]
	v_mfma_f32_16x16x32_bf16 v[38:41], v[182:185], v[158:161], v[38:41]
	v_mfma_f32_16x16x32_bf16 v[34:37], v[204:207], v[158:161], v[34:37]
	v_mfma_f32_16x16x32_bf16 v[22:25], v[182:185], v[166:169], v[22:25]
	v_mfma_f32_16x16x32_bf16 v[18:21], v[204:207], v[166:169], v[18:21]
	v_mfma_f32_16x16x32_bf16 v[6:9], v[182:185], v[174:177], v[6:9]
	v_mfma_f32_16x16x32_bf16 v[2:5], v[204:207], v[174:177], v[2:5]
	s_barrier
	s_add_u32 s88, s92, 0xc0000
	s_addc_u32 s89, s93, 0
	s_mov_b32 m0, s43
	ds_read_b128 v[146:149], v213 offset:32768
	ds_read_b128 v[150:153], v213 offset:33792
	ds_read_b128 v[154:157], v213 offset:34816
	ds_read_b128 v[158:161], v213 offset:35840
	ds_read_b128 v[162:165], v213 offset:36864
	ds_read_b128 v[166:169], v213 offset:37888
	ds_read_b128 v[170:173], v213 offset:38912
	ds_read_b128 v[174:177], v213 offset:39936
	global_load_lds_dwordx4 v190, s[88:89]
	s_mov_b32 m0, s44
	s_nop 0
	global_load_lds_dwordx4 v192, s[88:89]
	s_waitcnt lgkmcnt(8)
	s_barrier
	s_waitcnt lgkmcnt(0)
	v_mfma_f32_16x16x32_bf16 v[126:129], v[130:133], v[146:149], v[126:129]
	v_mfma_f32_16x16x32_bf16 v[122:125], v[138:141], v[146:149], v[122:125]
	v_mfma_f32_16x16x32_bf16 v[110:113], v[130:133], v[154:157], v[110:113]
	v_mfma_f32_16x16x32_bf16 v[106:109], v[138:141], v[154:157], v[106:109]
	v_mfma_f32_16x16x32_bf16 v[94:97], v[130:133], v[162:165], v[94:97]
	v_mfma_f32_16x16x32_bf16 v[90:93], v[138:141], v[162:165], v[90:93]
	v_mfma_f32_16x16x32_bf16 v[78:81], v[130:133], v[170:173], v[78:81]
	v_mfma_f32_16x16x32_bf16 v[74:77], v[138:141], v[170:173], v[74:77]
	v_mfma_f32_16x16x32_bf16 v[126:129], v[134:137], v[150:153], v[126:129]
	v_mfma_f32_16x16x32_bf16 v[122:125], v[142:145], v[150:153], v[122:125]
	v_mfma_f32_16x16x32_bf16 v[110:113], v[134:137], v[158:161], v[110:113]
	v_mfma_f32_16x16x32_bf16 v[106:109], v[142:145], v[158:161], v[106:109]
	v_mfma_f32_16x16x32_bf16 v[94:97], v[134:137], v[166:169], v[94:97]
	v_mfma_f32_16x16x32_bf16 v[90:93], v[142:145], v[166:169], v[90:93]
	v_mfma_f32_16x16x32_bf16 v[78:81], v[134:137], v[174:177], v[78:81]
	v_mfma_f32_16x16x32_bf16 v[74:77], v[142:145], v[174:177], v[74:77]
	s_barrier
	s_add_i32 s87, 0, 0x1c000
	v_add_u32_e32 v204, s87, v212
	s_add_i32 m0, s38, 0x18000
	ds_read_b128 v[178:181], v204
	ds_read_b128 v[182:185], v204 offset:1024
	ds_read_b128 v[200:203], v204 offset:2048
	ds_read_b128 v[204:207], v204 offset:3072
	s_add_u32 s98, s90, s40
	s_addc_u32 s99, s91, s41
	global_load_lds_dwordx4 v0, s[98:99]
	s_add_i32 m0, s38, 0x1a000
	s_nop 0
	global_load_lds_dwordx4 v194, s[98:99]
	s_barrier
	s_waitcnt lgkmcnt(0)
	v_mfma_f32_16x16x32_bf16 v[118:121], v[178:181], v[146:149], v[118:121]
	v_mfma_f32_16x16x32_bf16 v[114:117], v[200:203], v[146:149], v[114:117]
	v_mfma_f32_16x16x32_bf16 v[102:105], v[178:181], v[154:157], v[102:105]
	v_mfma_f32_16x16x32_bf16 v[98:101], v[200:203], v[154:157], v[98:101]
	v_mfma_f32_16x16x32_bf16 v[86:89], v[178:181], v[162:165], v[86:89]
	v_mfma_f32_16x16x32_bf16 v[82:85], v[200:203], v[162:165], v[82:85]
	v_mfma_f32_16x16x32_bf16 v[70:73], v[178:181], v[170:173], v[70:73]
	v_mfma_f32_16x16x32_bf16 v[66:69], v[200:203], v[170:173], v[66:69]
	v_mfma_f32_16x16x32_bf16 v[118:121], v[182:185], v[150:153], v[118:121]
	v_mfma_f32_16x16x32_bf16 v[114:117], v[204:207], v[150:153], v[114:117]
	v_mfma_f32_16x16x32_bf16 v[102:105], v[182:185], v[158:161], v[102:105]
	v_mfma_f32_16x16x32_bf16 v[98:101], v[204:207], v[158:161], v[98:101]
	v_mfma_f32_16x16x32_bf16 v[86:89], v[182:185], v[166:169], v[86:89]
	v_mfma_f32_16x16x32_bf16 v[82:85], v[204:207], v[166:169], v[82:85]
	v_mfma_f32_16x16x32_bf16 v[70:73], v[182:185], v[174:177], v[70:73]
	v_mfma_f32_16x16x32_bf16 v[66:69], v[204:207], v[174:177], v[66:69]
	s_mov_b32 m0, s60
	s_barrier
	ds_read_b128 v[146:149], v213 offset:49152
	ds_read_b128 v[150:153], v213 offset:50176
	ds_read_b128 v[154:157], v213 offset:51200
	ds_read_b128 v[158:161], v213 offset:52224
	ds_read_b128 v[162:165], v213 offset:53248
	ds_read_b128 v[166:169], v213 offset:54272
	ds_read_b128 v[170:173], v213 offset:55296
	ds_read_b128 v[174:177], v213 offset:56320
	s_add_u32 s98, s92, s40
	s_addc_u32 s99, s93, s41
	global_load_lds_dwordx4 v190, s[98:99]
	s_mov_b32 m0, s61
	s_nop 0
	global_load_lds_dwordx4 v192, s[98:99]
	s_waitcnt vmcnt(10)
	s_barrier
	s_waitcnt lgkmcnt(0)
	v_mfma_f32_16x16x32_bf16 v[62:65], v[130:133], v[146:149], v[62:65]
	v_mfma_f32_16x16x32_bf16 v[58:61], v[138:141], v[146:149], v[58:61]
	v_mfma_f32_16x16x32_bf16 v[46:49], v[130:133], v[154:157], v[46:49]
	v_mfma_f32_16x16x32_bf16 v[42:45], v[138:141], v[154:157], v[42:45]
	v_mfma_f32_16x16x32_bf16 v[30:33], v[130:133], v[162:165], v[30:33]
	v_mfma_f32_16x16x32_bf16 v[26:29], v[138:141], v[162:165], v[26:29]
	v_mfma_f32_16x16x32_bf16 v[14:17], v[130:133], v[170:173], v[14:17]
	v_mfma_f32_16x16x32_bf16 v[10:13], v[138:141], v[170:173], v[10:13]
	v_mfma_f32_16x16x32_bf16 v[62:65], v[134:137], v[150:153], v[62:65]
	v_mfma_f32_16x16x32_bf16 v[58:61], v[142:145], v[150:153], v[58:61]
	v_mfma_f32_16x16x32_bf16 v[46:49], v[134:137], v[158:161], v[46:49]
	v_mfma_f32_16x16x32_bf16 v[42:45], v[142:145], v[158:161], v[42:45]
	v_mfma_f32_16x16x32_bf16 v[30:33], v[134:137], v[166:169], v[30:33]
	v_mfma_f32_16x16x32_bf16 v[26:29], v[142:145], v[166:169], v[26:29]
	v_mfma_f32_16x16x32_bf16 v[14:17], v[134:137], v[174:177], v[14:17]
	v_mfma_f32_16x16x32_bf16 v[10:13], v[142:145], v[174:177], v[10:13]
	s_barrier
	s_add_u32 s88, s90, 0x40080
	s_addc_u32 s89, s91, 0
	s_add_i32 m0, s38, 0x1c000
	s_nop 0
	global_load_lds_dwordx4 v0, s[88:89]
	s_add_i32 m0, s38, 0x1e000
	s_nop 0
	global_load_lds_dwordx4 v194, s[88:89]
	ds_read_b128 v[130:133], v189
	ds_read_b128 v[134:137], v189 offset:1024
	ds_read_b128 v[138:141], v189 offset:2048
	ds_read_b128 v[142:145], v189 offset:3072
	s_waitcnt vmcnt(6)
	s_barrier
	v_mfma_f32_16x16x32_bf16 v[54:57], v[178:181], v[146:149], v[54:57]
	v_mfma_f32_16x16x32_bf16 v[50:53], v[200:203], v[146:149], v[50:53]
	v_mfma_f32_16x16x32_bf16 v[38:41], v[178:181], v[154:157], v[38:41]
	v_mfma_f32_16x16x32_bf16 v[34:37], v[200:203], v[154:157], v[34:37]
	v_mfma_f32_16x16x32_bf16 v[22:25], v[178:181], v[162:165], v[22:25]
	v_mfma_f32_16x16x32_bf16 v[18:21], v[200:203], v[162:165], v[18:21]
	v_mfma_f32_16x16x32_bf16 v[6:9], v[178:181], v[170:173], v[6:9]
	v_mfma_f32_16x16x32_bf16 v[2:5], v[200:203], v[170:173], v[2:5]
	v_mfma_f32_16x16x32_bf16 v[54:57], v[182:185], v[150:153], v[54:57]
	v_mfma_f32_16x16x32_bf16 v[50:53], v[204:207], v[150:153], v[50:53]
	v_mfma_f32_16x16x32_bf16 v[38:41], v[182:185], v[158:161], v[38:41]
	v_mfma_f32_16x16x32_bf16 v[34:37], v[204:207], v[158:161], v[34:37]
	v_mfma_f32_16x16x32_bf16 v[22:25], v[182:185], v[166:169], v[22:25]
	v_mfma_f32_16x16x32_bf16 v[18:21], v[204:207], v[166:169], v[18:21]
	v_mfma_f32_16x16x32_bf16 v[6:9], v[182:185], v[174:177], v[6:9]
	v_mfma_f32_16x16x32_bf16 v[2:5], v[204:207], v[174:177], v[2:5]
	s_add_i32 s78, s78, 2
	s_add_u32 s34, s34, 0x100
	s_addc_u32 s75, s75, 0
	s_mov_b64 s[88:89], s[4:5]
	s_add_u32 s4, s88, 0x100
	s_addc_u32 s5, s89, 0
	s_cmp_eq_u32 s78, 12
	s_cselect_b32 s93, s17, s5
	s_cselect_b32 s92, s16, s4
	s_cselect_b32 s91, s15, s75
	s_cselect_b32 s90, s23, s34
	s_cmp_gt_u32 s78, 13
	s_barrier
	s_cbranch_scc0 .LBB0_838
	s_waitcnt lgkmcnt(0)
	s_lshl_b32 s4, s22, 8
	v_mov_b32_e32 v186, v252
	s_add_i32 s4, s4, s47
	s_nop 0
	v_and_or_b32 v202, v186, 15, s4
	s_lshl_b32 s4, s86, 8
	s_or_b32 s4, s4, s55
	v_lshrrev_b32_e32 v130, 1, v186
	v_and_or_b32 v200, v130, 24, s4
	v_ashrrev_i32_e32 v201, 31, v200
	v_ashrrev_i32_e32 v203, 31, v202
	v_lshl_add_u64 v[204:205], v[200:201], 2, s[6:7]
	v_lshlrev_b64 v[130:131], 12, v[202:203]
	v_lshl_add_u64 v[130:131], v[204:205], 0, v[130:131]
	global_load_dwordx4 v[216:219], v[130:131], off offset:16
	global_load_dwordx4 v[220:223], v[130:131], off
	global_load_dwordx4 v[178:181], v[130:131], off offset:528
	global_load_dwordx4 v[182:185], v[130:131], off offset:512
	v_or_b32_e32 v210, 16, v202
	v_ashrrev_i32_e32 v211, 31, v210
	v_lshlrev_b64 v[130:131], 12, v[210:211]
	v_or_b32_e32 v208, 32, v202
	v_lshl_add_u64 v[130:131], v[204:205], 0, v[130:131]
	v_ashrrev_i32_e32 v209, 31, v208
	global_load_dwordx4 v[170:173], v[130:131], off offset:16
	global_load_dwordx4 v[174:177], v[130:131], off
	global_load_dwordx4 v[162:165], v[130:131], off offset:528
	global_load_dwordx4 v[166:169], v[130:131], off offset:512
	v_lshlrev_b64 v[130:131], 12, v[208:209]
	v_or_b32_e32 v206, 48, v202
	v_lshl_add_u64 v[130:131], v[204:205], 0, v[130:131]
	v_ashrrev_i32_e32 v207, 31, v206
	global_load_dwordx4 v[154:157], v[130:131], off offset:16
	global_load_dwordx4 v[158:161], v[130:131], off
	global_load_dwordx4 v[138:141], v[130:131], off offset:528
	global_load_dwordx4 v[142:145], v[130:131], off offset:512
	v_lshlrev_b64 v[130:131], 12, v[206:207]
	v_lshl_add_u64 v[134:135], v[204:205], 0, v[130:131]
	global_load_dwordx4 v[146:149], v[134:135], off offset:16
	global_load_dwordx4 v[150:153], v[134:135], off
	global_load_dwordx4 v[130:133], v[134:135], off offset:528
	s_nop 0
	global_load_dwordx4 v[134:137], v[134:135], off offset:512
	v_and_b32_e32 v186, 63, v186
	v_lshlrev_b32_e32 v187, 2, v186
	v_xor_b32_e32 v215, 64, v187
	v_xor_b32_e32 v214, 0x80, v187
	v_cmp_gt_u32_e32 vcc, 16, v186
	v_lshlrev_b64 v[186:187], 10, v[202:203]
	v_lshl_add_u64 v[186:187], v[186:187], 0, v[200:201]
	s_lshl_b32 s4, s86, 2
	s_ashr_i32 s5, s4, 31
	s_waitcnt vmcnt(0)
	v_pk_add_f32 v[124:125], v[124:125], v[218:219]
	v_pk_add_f32 v[128:129], v[128:129], v[222:223]
	v_pk_add_f32 v[126:127], v[126:127], v[220:221]
	v_pk_mul_f32 v[218:219], v[128:129], v[128:129]
	v_pk_mul_f32 v[220:221], v[126:127], v[126:127]
	v_pk_add_f32 v[122:123], v[122:123], v[216:217]
	v_lshl_add_u64 v[216:217], v[186:187], 2, s[12:13]
	v_add_f32_e32 v220, v220, v221
	v_add_f32_e32 v218, v218, v219
	global_store_dwordx4 v[216:217], v[126:129], off
	global_store_dwordx4 v[216:217], v[122:125], off offset:16
	v_add_f32_e32 v222, v220, v218
	v_pk_mul_f32 v[220:221], v[122:123], v[122:123]
	v_cvt_pk_bf16_f32 v126, v126, v127
	v_cvt_pk_bf16_f32 v127, v128, v129
	v_cvt_pk_bf16_f32 v128, v122, v123
	v_cvt_pk_bf16_f32 v129, v124, v125
	v_lshl_add_u64 v[122:123], v[186:187], 1, s[8:9]
	v_pk_add_f32 v[120:121], v[120:121], v[184:185]
	v_pk_add_f32 v[118:119], v[118:119], v[182:183]
	v_pk_mul_f32 v[218:219], v[124:125], v[124:125]
	global_store_dwordx4 v[122:123], v[126:129], off
	v_pk_mul_f32 v[124:125], v[120:121], v[120:121]
	v_pk_add_f32 v[116:117], v[116:117], v[180:181]
	v_pk_mul_f32 v[126:127], v[118:119], v[118:119]
	v_pk_add_f32 v[114:115], v[114:115], v[178:179]
	v_add_f32_e32 v126, v126, v127
	v_add_f32_e32 v124, v124, v125
	v_add_f32_e32 v128, v126, v124
	v_pk_mul_f32 v[124:125], v[116:117], v[116:117]
	v_pk_mul_f32 v[126:127], v[114:115], v[114:115]
	v_add_f32_e32 v220, v220, v221
	v_add_f32_e32 v218, v218, v219
	v_add_f32_e32 v126, v126, v127
	v_add_f32_e32 v124, v124, v125
	v_add_f32_e32 v218, v220, v218
	v_add_f32_e32 v124, v126, v124
	v_add_f32_e32 v218, v222, v218
	v_add_f32_e32 v124, v128, v124
	v_add_f32_e32 v124, v218, v124
	global_store_dwordx4 v[216:217], v[118:121], off offset:512
	global_store_dwordx4 v[216:217], v[114:117], off offset:528
	s_nop 0
	v_cvt_pk_bf16_f32 v118, v118, v119
	v_cvt_pk_bf16_f32 v119, v120, v121
	v_cvt_pk_bf16_f32 v120, v114, v115
	ds_bpermute_b32 v114, v215, v124
	v_cvt_pk_bf16_f32 v121, v116, v117
	global_store_dwordx4 v[122:123], v[118:121], off offset:256
	s_waitcnt lgkmcnt(0)
	v_add_f32_e32 v114, v124, v114
	ds_bpermute_b32 v115, v214, v114
	s_and_saveexec_b64 s[22:23], vcc
	s_cbranch_execz .LBB0_841
	v_lshlrev_b64 v[116:117], 6, v[202:203]
	v_lshl_add_u64 v[116:117], s[10:11], 0, v[116:117]
	v_lshl_add_u64 v[116:117], s[4:5], 2, v[116:117]
	s_lshl_b32 s34, s45, 2
	v_lshl_add_u64 v[116:117], v[116:117], 0, s[34:35]
	s_waitcnt lgkmcnt(0)
	v_add_f32_e32 v114, v114, v115
	global_store_dword v[116:117], v114, off

.LBB0_1089:
	s_add_u32 s34, s84, 0x100
	s_addc_u32 s78, s85, 0
	s_mov_b32 s79, -2
	s_waitcnt lgkmcnt(0)
	s_add_i32 s90, 0, 0x10000
	v_add_u32_e32 v142, s90, v212
	v_add_u32_e32 v189, 0x10000, v212
	ds_read_b128 v[130:133], v142
	ds_read_b128 v[134:137], v142 offset:1024
	ds_read_b128 v[138:141], v142 offset:2048
	ds_read_b128 v[142:145], v142 offset:3072
	s_add_u32 s84, s16, 0x100
	s_addc_u32 s85, s17, 0
	s_cmp_eq_u32 s79, 40
	s_cselect_b32 s89, s5, s85
	s_cselect_b32 s88, s4, s84
	s_cselect_b32 s87, s7, s78
	s_cselect_b32 s86, s6, s34
	v_lshl_add_u64 v[178:179], s[16:17], 0, v[196:197]
	s_add_i32 m0, s39, 0xc000
	ds_read_b128 v[146:149], v213
	ds_read_b128 v[150:153], v213 offset:1024
	ds_read_b128 v[154:157], v213 offset:2048
	ds_read_b128 v[158:161], v213 offset:3072
	ds_read_b128 v[162:165], v213 offset:4096
	ds_read_b128 v[166:169], v213 offset:5120
	ds_read_b128 v[170:173], v213 offset:6144
	ds_read_b128 v[174:177], v213 offset:7168
	global_load_lds_dwordx4 v[178:179], off
	s_add_i32 m0, s39, 0xe000
	v_lshl_add_u64 v[178:179], s[16:17], 0, v[198:199]
	global_load_lds_dwordx4 v[178:179], off
	s_waitcnt lgkmcnt(8)
	s_barrier
	s_waitcnt lgkmcnt(0)
	v_mfma_f32_16x16x32_bf16 v[126:129], v[130:133], v[146:149], 0
	v_mfma_f32_16x16x32_bf16 v[122:125], v[138:141], v[146:149], 0
	v_mfma_f32_16x16x32_bf16 v[110:113], v[130:133], v[154:157], 0
	v_mfma_f32_16x16x32_bf16 v[106:109], v[138:141], v[154:157], 0
	v_mfma_f32_16x16x32_bf16 v[94:97], v[130:133], v[162:165], 0
	v_mfma_f32_16x16x32_bf16 v[90:93], v[138:141], v[162:165], 0
	v_mfma_f32_16x16x32_bf16 v[78:81], v[130:133], v[170:173], 0
	v_mfma_f32_16x16x32_bf16 v[74:77], v[138:141], v[170:173], 0
	v_mfma_f32_16x16x32_bf16 v[126:129], v[134:137], v[150:153], v[126:129]
	v_mfma_f32_16x16x32_bf16 v[122:125], v[142:145], v[150:153], v[122:125]
	v_mfma_f32_16x16x32_bf16 v[110:113], v[134:137], v[158:161], v[110:113]
	v_mfma_f32_16x16x32_bf16 v[106:109], v[142:145], v[158:161], v[106:109]
	v_mfma_f32_16x16x32_bf16 v[94:97], v[134:137], v[166:169], v[94:97]
	v_mfma_f32_16x16x32_bf16 v[90:93], v[142:145], v[166:169], v[90:93]
	v_mfma_f32_16x16x32_bf16 v[78:81], v[134:137], v[174:177], v[78:81]
	v_mfma_f32_16x16x32_bf16 v[74:77], v[142:145], v[174:177], v[74:77]
	s_barrier
	ds_read_b128 v[178:181], v189 offset:16384
	ds_read_b128 v[182:185], v189 offset:17408
	ds_read_b128 v[200:203], v189 offset:18432
	ds_read_b128 v[204:207], v189 offset:19456
	s_add_i32 m0, s38, 0x10000
	s_nop 0
	global_load_lds_dwordx4 v0, s[86:87]
	s_add_i32 m0, s38, 0x12000
	s_nop 0
	global_load_lds_dwordx4 v194, s[86:87]
	s_barrier
	s_waitcnt lgkmcnt(0)
	v_mfma_f32_16x16x32_bf16 v[118:121], v[178:181], v[146:149], 0
	v_mfma_f32_16x16x32_bf16 v[114:117], v[200:203], v[146:149], 0
	v_mfma_f32_16x16x32_bf16 v[102:105], v[178:181], v[154:157], 0
	v_mfma_f32_16x16x32_bf16 v[98:101], v[200:203], v[154:157], 0
	v_mfma_f32_16x16x32_bf16 v[86:89], v[178:181], v[162:165], 0
	v_mfma_f32_16x16x32_bf16 v[82:85], v[200:203], v[162:165], 0
	v_mfma_f32_16x16x32_bf16 v[70:73], v[178:181], v[170:173], 0
	v_mfma_f32_16x16x32_bf16 v[66:69], v[200:203], v[170:173], 0
	v_mfma_f32_16x16x32_bf16 v[118:121], v[182:185], v[150:153], v[118:121]
	v_mfma_f32_16x16x32_bf16 v[114:117], v[204:207], v[150:153], v[114:117]
	v_mfma_f32_16x16x32_bf16 v[102:105], v[182:185], v[158:161], v[102:105]
	v_mfma_f32_16x16x32_bf16 v[98:101], v[204:207], v[158:161], v[98:101]
	v_mfma_f32_16x16x32_bf16 v[86:89], v[182:185], v[166:169], v[86:89]
	v_mfma_f32_16x16x32_bf16 v[82:85], v[204:207], v[166:169], v[82:85]
	v_mfma_f32_16x16x32_bf16 v[70:73], v[182:185], v[174:177], v[70:73]
	v_mfma_f32_16x16x32_bf16 v[66:69], v[204:207], v[174:177], v[66:69]
	s_mov_b32 m0, s39
	s_mov_b64 s[100:101], s[88:89]
	s_barrier
	ds_read_b128 v[146:149], v213 offset:16384
	ds_read_b128 v[150:153], v213 offset:17408
	ds_read_b128 v[154:157], v213 offset:18432
	ds_read_b128 v[158:161], v213 offset:19456
	ds_read_b128 v[162:165], v213 offset:20480
	ds_read_b128 v[166:169], v213 offset:21504
	ds_read_b128 v[170:173], v213 offset:22528
	ds_read_b128 v[174:177], v213 offset:23552
	global_load_lds_dwordx4 v190, s[100:101]
	s_mov_b32 m0, s42
	s_nop 0
	global_load_lds_dwordx4 v192, s[100:101]
	s_waitcnt vmcnt(10)
	s_barrier
	s_waitcnt lgkmcnt(0)
	v_mfma_f32_16x16x32_bf16 v[62:65], v[130:133], v[146:149], 0
	v_mfma_f32_16x16x32_bf16 v[58:61], v[138:141], v[146:149], 0
	v_mfma_f32_16x16x32_bf16 v[46:49], v[130:133], v[154:157], 0
	v_mfma_f32_16x16x32_bf16 v[42:45], v[138:141], v[154:157], 0
	v_mfma_f32_16x16x32_bf16 v[30:33], v[130:133], v[162:165], 0
	v_mfma_f32_16x16x32_bf16 v[26:29], v[138:141], v[162:165], 0
	v_mfma_f32_16x16x32_bf16 v[14:17], v[130:133], v[170:173], 0
	v_mfma_f32_16x16x32_bf16 v[10:13], v[138:141], v[170:173], 0
	v_mfma_f32_16x16x32_bf16 v[62:65], v[134:137], v[150:153], v[62:65]
	v_mfma_f32_16x16x32_bf16 v[58:61], v[142:145], v[150:153], v[58:61]
	v_mfma_f32_16x16x32_bf16 v[46:49], v[134:137], v[158:161], v[46:49]
	v_mfma_f32_16x16x32_bf16 v[42:45], v[142:145], v[158:161], v[42:45]
	v_mfma_f32_16x16x32_bf16 v[30:33], v[134:137], v[166:169], v[30:33]
	v_mfma_f32_16x16x32_bf16 v[26:29], v[142:145], v[166:169], v[26:29]
	v_mfma_f32_16x16x32_bf16 v[14:17], v[134:137], v[174:177], v[14:17]
	v_mfma_f32_16x16x32_bf16 v[10:13], v[142:145], v[174:177], v[10:13]
	s_barrier
	s_add_u32 s16, s86, 0xb0000
	s_addc_u32 s17, s87, 0
	s_add_i32 m0, s38, 0x14000
	s_nop 0
	global_load_lds_dwordx4 v0, s[16:17]
	s_add_i32 m0, s38, 0x16000
	s_nop 0
	global_load_lds_dwordx4 v194, s[16:17]
	s_add_i32 s90, 0, 0x18000
	v_add_u32_e32 v142, s90, v212
	ds_read_b128 v[130:133], v142
	ds_read_b128 v[134:137], v142 offset:1024
	ds_read_b128 v[138:141], v142 offset:2048
	ds_read_b128 v[142:145], v142 offset:3072
	s_waitcnt vmcnt(6)
	s_barrier
	v_mfma_f32_16x16x32_bf16 v[54:57], v[178:181], v[146:149], 0
	v_mfma_f32_16x16x32_bf16 v[50:53], v[200:203], v[146:149], 0
	v_mfma_f32_16x16x32_bf16 v[38:41], v[178:181], v[154:157], 0
	v_mfma_f32_16x16x32_bf16 v[34:37], v[200:203], v[154:157], 0
	v_mfma_f32_16x16x32_bf16 v[22:25], v[178:181], v[162:165], 0
	v_mfma_f32_16x16x32_bf16 v[18:21], v[200:203], v[162:165], 0
	v_mfma_f32_16x16x32_bf16 v[6:9], v[178:181], v[170:173], 0
	v_mfma_f32_16x16x32_bf16 v[2:5], v[200:203], v[170:173], 0
	v_mfma_f32_16x16x32_bf16 v[54:57], v[182:185], v[150:153], v[54:57]
	v_mfma_f32_16x16x32_bf16 v[50:53], v[204:207], v[150:153], v[50:53]
	v_mfma_f32_16x16x32_bf16 v[38:41], v[182:185], v[158:161], v[38:41]
	v_mfma_f32_16x16x32_bf16 v[34:37], v[204:207], v[158:161], v[34:37]
	v_mfma_f32_16x16x32_bf16 v[22:25], v[182:185], v[166:169], v[22:25]
	v_mfma_f32_16x16x32_bf16 v[18:21], v[204:207], v[166:169], v[18:21]
	v_mfma_f32_16x16x32_bf16 v[6:9], v[182:185], v[174:177], v[6:9]
	v_mfma_f32_16x16x32_bf16 v[2:5], v[204:207], v[174:177], v[2:5]
	s_barrier
	s_add_u32 s16, s88, 0xb0000
	s_addc_u32 s17, s89, 0
	s_mov_b32 m0, s43
	ds_read_b128 v[146:149], v213 offset:32768
	ds_read_b128 v[150:153], v213 offset:33792
	ds_read_b128 v[154:157], v213 offset:34816
	ds_read_b128 v[158:161], v213 offset:35840
	ds_read_b128 v[162:165], v213 offset:36864
	ds_read_b128 v[166:169], v213 offset:37888
	ds_read_b128 v[170:173], v213 offset:38912
	ds_read_b128 v[174:177], v213 offset:39936
	global_load_lds_dwordx4 v190, s[16:17]
	s_mov_b32 m0, s44
	s_nop 0
	global_load_lds_dwordx4 v192, s[16:17]
	s_waitcnt lgkmcnt(8)
	s_barrier
	s_waitcnt lgkmcnt(0)
	v_mfma_f32_16x16x32_bf16 v[126:129], v[130:133], v[146:149], v[126:129]
	v_mfma_f32_16x16x32_bf16 v[122:125], v[138:141], v[146:149], v[122:125]
	v_mfma_f32_16x16x32_bf16 v[110:113], v[130:133], v[154:157], v[110:113]
	v_mfma_f32_16x16x32_bf16 v[106:109], v[138:141], v[154:157], v[106:109]
	v_mfma_f32_16x16x32_bf16 v[94:97], v[130:133], v[162:165], v[94:97]
	v_mfma_f32_16x16x32_bf16 v[90:93], v[138:141], v[162:165], v[90:93]
	v_mfma_f32_16x16x32_bf16 v[78:81], v[130:133], v[170:173], v[78:81]
	v_mfma_f32_16x16x32_bf16 v[74:77], v[138:141], v[170:173], v[74:77]
	v_mfma_f32_16x16x32_bf16 v[126:129], v[134:137], v[150:153], v[126:129]
	v_mfma_f32_16x16x32_bf16 v[122:125], v[142:145], v[150:153], v[122:125]
	v_mfma_f32_16x16x32_bf16 v[110:113], v[134:137], v[158:161], v[110:113]
	v_mfma_f32_16x16x32_bf16 v[106:109], v[142:145], v[158:161], v[106:109]
	v_mfma_f32_16x16x32_bf16 v[94:97], v[134:137], v[166:169], v[94:97]
	v_mfma_f32_16x16x32_bf16 v[90:93], v[142:145], v[166:169], v[90:93]
	v_mfma_f32_16x16x32_bf16 v[78:81], v[134:137], v[174:177], v[78:81]
	v_mfma_f32_16x16x32_bf16 v[74:77], v[142:145], v[174:177], v[74:77]
	s_barrier
	s_add_i32 s88, 0, 0x1c000
	v_add_u32_e32 v204, s88, v212
	s_add_i32 m0, s38, 0x18000
	ds_read_b128 v[178:181], v204
	ds_read_b128 v[182:185], v204 offset:1024
	ds_read_b128 v[200:203], v204 offset:2048
	ds_read_b128 v[204:207], v204 offset:3072
	s_add_u32 s98, s86, s40
	s_addc_u32 s99, s87, s41
	global_load_lds_dwordx4 v0, s[98:99]
	s_add_i32 m0, s38, 0x1a000
	s_nop 0
	global_load_lds_dwordx4 v194, s[98:99]
	s_barrier
	s_waitcnt lgkmcnt(0)
	v_mfma_f32_16x16x32_bf16 v[118:121], v[178:181], v[146:149], v[118:121]
	v_mfma_f32_16x16x32_bf16 v[114:117], v[200:203], v[146:149], v[114:117]
	v_mfma_f32_16x16x32_bf16 v[102:105], v[178:181], v[154:157], v[102:105]
	v_mfma_f32_16x16x32_bf16 v[98:101], v[200:203], v[154:157], v[98:101]
	v_mfma_f32_16x16x32_bf16 v[86:89], v[178:181], v[162:165], v[86:89]
	v_mfma_f32_16x16x32_bf16 v[82:85], v[200:203], v[162:165], v[82:85]
	v_mfma_f32_16x16x32_bf16 v[70:73], v[178:181], v[170:173], v[70:73]
	v_mfma_f32_16x16x32_bf16 v[66:69], v[200:203], v[170:173], v[66:69]
	v_mfma_f32_16x16x32_bf16 v[118:121], v[182:185], v[150:153], v[118:121]
	v_mfma_f32_16x16x32_bf16 v[114:117], v[204:207], v[150:153], v[114:117]
	v_mfma_f32_16x16x32_bf16 v[102:105], v[182:185], v[158:161], v[102:105]
	v_mfma_f32_16x16x32_bf16 v[98:101], v[204:207], v[158:161], v[98:101]
	v_mfma_f32_16x16x32_bf16 v[86:89], v[182:185], v[166:169], v[86:89]
	v_mfma_f32_16x16x32_bf16 v[82:85], v[204:207], v[166:169], v[82:85]
	v_mfma_f32_16x16x32_bf16 v[70:73], v[182:185], v[174:177], v[70:73]
	v_mfma_f32_16x16x32_bf16 v[66:69], v[204:207], v[174:177], v[66:69]
	s_mov_b32 m0, s60
	s_barrier
	ds_read_b128 v[146:149], v213 offset:49152
	ds_read_b128 v[150:153], v213 offset:50176
	ds_read_b128 v[154:157], v213 offset:51200
	ds_read_b128 v[158:161], v213 offset:52224
	ds_read_b128 v[162:165], v213 offset:53248
	ds_read_b128 v[166:169], v213 offset:54272
	ds_read_b128 v[170:173], v213 offset:55296
	ds_read_b128 v[174:177], v213 offset:56320
	s_add_u32 s98, s100, s40
	s_addc_u32 s99, s101, s41
	global_load_lds_dwordx4 v190, s[98:99]
	s_mov_b32 m0, s61
	s_nop 0
	global_load_lds_dwordx4 v192, s[98:99]
	s_waitcnt vmcnt(10)
	s_barrier
	s_waitcnt lgkmcnt(0)
	v_mfma_f32_16x16x32_bf16 v[62:65], v[130:133], v[146:149], v[62:65]
	v_mfma_f32_16x16x32_bf16 v[58:61], v[138:141], v[146:149], v[58:61]
	v_mfma_f32_16x16x32_bf16 v[46:49], v[130:133], v[154:157], v[46:49]
	v_mfma_f32_16x16x32_bf16 v[42:45], v[138:141], v[154:157], v[42:45]
	v_mfma_f32_16x16x32_bf16 v[30:33], v[130:133], v[162:165], v[30:33]
	v_mfma_f32_16x16x32_bf16 v[26:29], v[138:141], v[162:165], v[26:29]
	v_mfma_f32_16x16x32_bf16 v[14:17], v[130:133], v[170:173], v[14:17]
	v_mfma_f32_16x16x32_bf16 v[10:13], v[138:141], v[170:173], v[10:13]
	v_mfma_f32_16x16x32_bf16 v[62:65], v[134:137], v[150:153], v[62:65]
	v_mfma_f32_16x16x32_bf16 v[58:61], v[142:145], v[150:153], v[58:61]
	v_mfma_f32_16x16x32_bf16 v[46:49], v[134:137], v[158:161], v[46:49]
	v_mfma_f32_16x16x32_bf16 v[42:45], v[142:145], v[158:161], v[42:45]
	v_mfma_f32_16x16x32_bf16 v[30:33], v[134:137], v[166:169], v[30:33]
	v_mfma_f32_16x16x32_bf16 v[26:29], v[142:145], v[166:169], v[26:29]
	v_mfma_f32_16x16x32_bf16 v[14:17], v[134:137], v[174:177], v[14:17]
	v_mfma_f32_16x16x32_bf16 v[10:13], v[142:145], v[174:177], v[10:13]
	s_barrier
	s_add_u32 s16, s86, 0xb0080
	s_addc_u32 s17, s87, 0
	s_add_i32 m0, s38, 0x1c000
	s_nop 0
	global_load_lds_dwordx4 v0, s[16:17]
	s_add_i32 m0, s38, 0x1e000
	s_nop 0
	global_load_lds_dwordx4 v194, s[16:17]
	ds_read_b128 v[130:133], v189
	ds_read_b128 v[134:137], v189 offset:1024
	ds_read_b128 v[138:141], v189 offset:2048
	ds_read_b128 v[142:145], v189 offset:3072
	s_waitcnt vmcnt(6)
	s_barrier
	v_mfma_f32_16x16x32_bf16 v[54:57], v[178:181], v[146:149], v[54:57]
	v_mfma_f32_16x16x32_bf16 v[50:53], v[200:203], v[146:149], v[50:53]
	v_mfma_f32_16x16x32_bf16 v[38:41], v[178:181], v[154:157], v[38:41]
	v_mfma_f32_16x16x32_bf16 v[34:37], v[200:203], v[154:157], v[34:37]
	v_mfma_f32_16x16x32_bf16 v[22:25], v[178:181], v[162:165], v[22:25]
	v_mfma_f32_16x16x32_bf16 v[18:21], v[200:203], v[162:165], v[18:21]
	v_mfma_f32_16x16x32_bf16 v[6:9], v[178:181], v[170:173], v[6:9]
	v_mfma_f32_16x16x32_bf16 v[2:5], v[200:203], v[170:173], v[2:5]
	v_mfma_f32_16x16x32_bf16 v[54:57], v[182:185], v[150:153], v[54:57]
	v_mfma_f32_16x16x32_bf16 v[50:53], v[204:207], v[150:153], v[50:53]
	v_mfma_f32_16x16x32_bf16 v[38:41], v[182:185], v[158:161], v[38:41]
	v_mfma_f32_16x16x32_bf16 v[34:37], v[204:207], v[158:161], v[34:37]
	v_mfma_f32_16x16x32_bf16 v[22:25], v[182:185], v[166:169], v[22:25]
	v_mfma_f32_16x16x32_bf16 v[18:21], v[204:207], v[166:169], v[18:21]
	v_mfma_f32_16x16x32_bf16 v[6:9], v[182:185], v[174:177], v[6:9]
	v_mfma_f32_16x16x32_bf16 v[2:5], v[204:207], v[174:177], v[2:5]
	s_add_i32 s79, s79, 2
	s_add_u32 s34, s34, 0x100
	s_addc_u32 s78, s78, 0
	s_mov_b64 s[16:17], s[84:85]
	s_add_u32 s84, s16, 0x100
	s_addc_u32 s85, s17, 0
	s_cmp_eq_u32 s79, 40
	s_cselect_b32 s89, s5, s85
	s_cselect_b32 s88, s4, s84
	s_cselect_b32 s87, s7, s78
	s_cselect_b32 s86, s6, s34
	s_cmp_gt_u32 s79, 41
	s_barrier
.LBB0_1090:
	v_lshl_add_u64 v[178:179], s[16:17], 0, v[196:197]
	s_add_i32 m0, s39, 0xc000
	ds_read_b128 v[146:149], v213
	ds_read_b128 v[150:153], v213 offset:1024
	ds_read_b128 v[154:157], v213 offset:2048
	ds_read_b128 v[158:161], v213 offset:3072
	ds_read_b128 v[162:165], v213 offset:4096
	ds_read_b128 v[166:169], v213 offset:5120
	ds_read_b128 v[170:173], v213 offset:6144
	ds_read_b128 v[174:177], v213 offset:7168
	global_load_lds_dwordx4 v[178:179], off
	s_add_i32 m0, s39, 0xe000
	v_lshl_add_u64 v[178:179], s[16:17], 0, v[198:199]
	global_load_lds_dwordx4 v[178:179], off
	s_waitcnt lgkmcnt(8)
	s_barrier
	s_waitcnt lgkmcnt(0)
	v_mfma_f32_16x16x32_bf16 v[126:129], v[130:133], v[146:149], v[126:129]
	v_mfma_f32_16x16x32_bf16 v[122:125], v[138:141], v[146:149], v[122:125]
	v_mfma_f32_16x16x32_bf16 v[110:113], v[130:133], v[154:157], v[110:113]
	v_mfma_f32_16x16x32_bf16 v[106:109], v[138:141], v[154:157], v[106:109]
	v_mfma_f32_16x16x32_bf16 v[94:97], v[130:133], v[162:165], v[94:97]
	v_mfma_f32_16x16x32_bf16 v[90:93], v[138:141], v[162:165], v[90:93]
	v_mfma_f32_16x16x32_bf16 v[78:81], v[130:133], v[170:173], v[78:81]
	v_mfma_f32_16x16x32_bf16 v[74:77], v[138:141], v[170:173], v[74:77]
	v_mfma_f32_16x16x32_bf16 v[126:129], v[134:137], v[150:153], v[126:129]
	v_mfma_f32_16x16x32_bf16 v[122:125], v[142:145], v[150:153], v[122:125]
	v_mfma_f32_16x16x32_bf16 v[110:113], v[134:137], v[158:161], v[110:113]
	v_mfma_f32_16x16x32_bf16 v[106:109], v[142:145], v[158:161], v[106:109]
	v_mfma_f32_16x16x32_bf16 v[94:97], v[134:137], v[166:169], v[94:97]
	v_mfma_f32_16x16x32_bf16 v[90:93], v[142:145], v[166:169], v[90:93]
	v_mfma_f32_16x16x32_bf16 v[78:81], v[134:137], v[174:177], v[78:81]
	v_mfma_f32_16x16x32_bf16 v[74:77], v[142:145], v[174:177], v[74:77]
	s_barrier
	ds_read_b128 v[178:181], v189 offset:16384
	ds_read_b128 v[182:185], v189 offset:17408
	ds_read_b128 v[200:203], v189 offset:18432
	ds_read_b128 v[204:207], v189 offset:19456
	s_add_i32 m0, s38, 0x10000
	s_nop 0
	global_load_lds_dwordx4 v0, s[86:87]
	s_add_i32 m0, s38, 0x12000
	s_nop 0
	global_load_lds_dwordx4 v194, s[86:87]
	s_barrier
	s_waitcnt lgkmcnt(0)
	v_mfma_f32_16x16x32_bf16 v[118:121], v[178:181], v[146:149], v[118:121]
	v_mfma_f32_16x16x32_bf16 v[114:117], v[200:203], v[146:149], v[114:117]
	v_mfma_f32_16x16x32_bf16 v[102:105], v[178:181], v[154:157], v[102:105]
	v_mfma_f32_16x16x32_bf16 v[98:101], v[200:203], v[154:157], v[98:101]
	v_mfma_f32_16x16x32_bf16 v[86:89], v[178:181], v[162:165], v[86:89]
	v_mfma_f32_16x16x32_bf16 v[82:85], v[200:203], v[162:165], v[82:85]
	v_mfma_f32_16x16x32_bf16 v[70:73], v[178:181], v[170:173], v[70:73]
	v_mfma_f32_16x16x32_bf16 v[66:69], v[200:203], v[170:173], v[66:69]
	v_mfma_f32_16x16x32_bf16 v[118:121], v[182:185], v[150:153], v[118:121]
	v_mfma_f32_16x16x32_bf16 v[114:117], v[204:207], v[150:153], v[114:117]
	v_mfma_f32_16x16x32_bf16 v[102:105], v[182:185], v[158:161], v[102:105]
	v_mfma_f32_16x16x32_bf16 v[98:101], v[204:207], v[158:161], v[98:101]
	v_mfma_f32_16x16x32_bf16 v[86:89], v[182:185], v[166:169], v[86:89]
	v_mfma_f32_16x16x32_bf16 v[82:85], v[204:207], v[166:169], v[82:85]
	v_mfma_f32_16x16x32_bf16 v[70:73], v[182:185], v[174:177], v[70:73]
	v_mfma_f32_16x16x32_bf16 v[66:69], v[204:207], v[174:177], v[66:69]
	s_mov_b32 m0, s39
	s_mov_b64 s[100:101], s[88:89]
	s_barrier
	ds_read_b128 v[146:149], v213 offset:16384
	ds_read_b128 v[150:153], v213 offset:17408
	ds_read_b128 v[154:157], v213 offset:18432
	ds_read_b128 v[158:161], v213 offset:19456
	ds_read_b128 v[162:165], v213 offset:20480
	ds_read_b128 v[166:169], v213 offset:21504
	ds_read_b128 v[170:173], v213 offset:22528
	ds_read_b128 v[174:177], v213 offset:23552
	global_load_lds_dwordx4 v190, s[100:101]
	s_mov_b32 m0, s42
	s_nop 0
	global_load_lds_dwordx4 v192, s[100:101]
	s_waitcnt vmcnt(10)
	s_barrier
	s_waitcnt lgkmcnt(0)
	v_mfma_f32_16x16x32_bf16 v[62:65], v[130:133], v[146:149], v[62:65]
	v_mfma_f32_16x16x32_bf16 v[58:61], v[138:141], v[146:149], v[58:61]
	v_mfma_f32_16x16x32_bf16 v[46:49], v[130:133], v[154:157], v[46:49]
	v_mfma_f32_16x16x32_bf16 v[42:45], v[138:141], v[154:157], v[42:45]
	v_mfma_f32_16x16x32_bf16 v[30:33], v[130:133], v[162:165], v[30:33]
	v_mfma_f32_16x16x32_bf16 v[26:29], v[138:141], v[162:165], v[26:29]
	v_mfma_f32_16x16x32_bf16 v[14:17], v[130:133], v[170:173], v[14:17]
	v_mfma_f32_16x16x32_bf16 v[10:13], v[138:141], v[170:173], v[10:13]
	v_mfma_f32_16x16x32_bf16 v[62:65], v[134:137], v[150:153], v[62:65]
	v_mfma_f32_16x16x32_bf16 v[58:61], v[142:145], v[150:153], v[58:61]
	v_mfma_f32_16x16x32_bf16 v[46:49], v[134:137], v[158:161], v[46:49]
	v_mfma_f32_16x16x32_bf16 v[42:45], v[142:145], v[158:161], v[42:45]
	v_mfma_f32_16x16x32_bf16 v[30:33], v[134:137], v[166:169], v[30:33]
	v_mfma_f32_16x16x32_bf16 v[26:29], v[142:145], v[166:169], v[26:29]
	v_mfma_f32_16x16x32_bf16 v[14:17], v[134:137], v[174:177], v[14:17]
	v_mfma_f32_16x16x32_bf16 v[10:13], v[142:145], v[174:177], v[10:13]
	s_barrier
	s_add_u32 s16, s86, 0xb0000
	s_addc_u32 s17, s87, 0
	s_add_i32 m0, s38, 0x14000
	s_nop 0
	global_load_lds_dwordx4 v0, s[16:17]
	s_add_i32 m0, s38, 0x16000
	s_nop 0
	global_load_lds_dwordx4 v194, s[16:17]
	s_add_i32 s90, 0, 0x18000
	v_add_u32_e32 v142, s90, v212
	ds_read_b128 v[130:133], v142
	ds_read_b128 v[134:137], v142 offset:1024
	ds_read_b128 v[138:141], v142 offset:2048
	ds_read_b128 v[142:145], v142 offset:3072
	s_waitcnt vmcnt(6)
	s_barrier
	v_mfma_f32_16x16x32_bf16 v[54:57], v[178:181], v[146:149], v[54:57]
	v_mfma_f32_16x16x32_bf16 v[50:53], v[200:203], v[146:149], v[50:53]
	v_mfma_f32_16x16x32_bf16 v[38:41], v[178:181], v[154:157], v[38:41]
	v_mfma_f32_16x16x32_bf16 v[34:37], v[200:203], v[154:157], v[34:37]
	v_mfma_f32_16x16x32_bf16 v[22:25], v[178:181], v[162:165], v[22:25]
	v_mfma_f32_16x16x32_bf16 v[18:21], v[200:203], v[162:165], v[18:21]
	v_mfma_f32_16x16x32_bf16 v[6:9], v[178:181], v[170:173], v[6:9]
	v_mfma_f32_16x16x32_bf16 v[2:5], v[200:203], v[170:173], v[2:5]
	v_mfma_f32_16x16x32_bf16 v[54:57], v[182:185], v[150:153], v[54:57]
	v_mfma_f32_16x16x32_bf16 v[50:53], v[204:207], v[150:153], v[50:53]
	v_mfma_f32_16x16x32_bf16 v[38:41], v[182:185], v[158:161], v[38:41]
	v_mfma_f32_16x16x32_bf16 v[34:37], v[204:207], v[158:161], v[34:37]
	v_mfma_f32_16x16x32_bf16 v[22:25], v[182:185], v[166:169], v[22:25]
	v_mfma_f32_16x16x32_bf16 v[18:21], v[204:207], v[166:169], v[18:21]
	v_mfma_f32_16x16x32_bf16 v[6:9], v[182:185], v[174:177], v[6:9]
	v_mfma_f32_16x16x32_bf16 v[2:5], v[204:207], v[174:177], v[2:5]
	s_barrier
	s_add_u32 s16, s88, 0xb0000
	s_addc_u32 s17, s89, 0
	s_mov_b32 m0, s43
	ds_read_b128 v[146:149], v213 offset:32768
	ds_read_b128 v[150:153], v213 offset:33792
	ds_read_b128 v[154:157], v213 offset:34816
	ds_read_b128 v[158:161], v213 offset:35840
	ds_read_b128 v[162:165], v213 offset:36864
	ds_read_b128 v[166:169], v213 offset:37888
	ds_read_b128 v[170:173], v213 offset:38912
	ds_read_b128 v[174:177], v213 offset:39936
	global_load_lds_dwordx4 v190, s[16:17]
	s_mov_b32 m0, s44
	s_nop 0
	global_load_lds_dwordx4 v192, s[16:17]
	s_waitcnt lgkmcnt(8)
	s_barrier
	s_waitcnt lgkmcnt(0)
	v_mfma_f32_16x16x32_bf16 v[126:129], v[130:133], v[146:149], v[126:129]
	v_mfma_f32_16x16x32_bf16 v[122:125], v[138:141], v[146:149], v[122:125]
	v_mfma_f32_16x16x32_bf16 v[110:113], v[130:133], v[154:157], v[110:113]
	v_mfma_f32_16x16x32_bf16 v[106:109], v[138:141], v[154:157], v[106:109]
	v_mfma_f32_16x16x32_bf16 v[94:97], v[130:133], v[162:165], v[94:97]
	v_mfma_f32_16x16x32_bf16 v[90:93], v[138:141], v[162:165], v[90:93]
	v_mfma_f32_16x16x32_bf16 v[78:81], v[130:133], v[170:173], v[78:81]
	v_mfma_f32_16x16x32_bf16 v[74:77], v[138:141], v[170:173], v[74:77]
	v_mfma_f32_16x16x32_bf16 v[126:129], v[134:137], v[150:153], v[126:129]
	v_mfma_f32_16x16x32_bf16 v[122:125], v[142:145], v[150:153], v[122:125]
	v_mfma_f32_16x16x32_bf16 v[110:113], v[134:137], v[158:161], v[110:113]
	v_mfma_f32_16x16x32_bf16 v[106:109], v[142:145], v[158:161], v[106:109]
	v_mfma_f32_16x16x32_bf16 v[94:97], v[134:137], v[166:169], v[94:97]
	v_mfma_f32_16x16x32_bf16 v[90:93], v[142:145], v[166:169], v[90:93]
	v_mfma_f32_16x16x32_bf16 v[78:81], v[134:137], v[174:177], v[78:81]
	v_mfma_f32_16x16x32_bf16 v[74:77], v[142:145], v[174:177], v[74:77]
	s_barrier
	s_add_i32 s88, 0, 0x1c000
	v_add_u32_e32 v204, s88, v212
	s_add_i32 m0, s38, 0x18000
	ds_read_b128 v[178:181], v204
	ds_read_b128 v[182:185], v204 offset:1024
	ds_read_b128 v[200:203], v204 offset:2048
	ds_read_b128 v[204:207], v204 offset:3072
	s_add_u32 s98, s86, s40
	s_addc_u32 s99, s87, s41
	global_load_lds_dwordx4 v0, s[98:99]
	s_add_i32 m0, s38, 0x1a000
	s_nop 0
	global_load_lds_dwordx4 v194, s[98:99]
	s_barrier
	s_waitcnt lgkmcnt(0)
	v_mfma_f32_16x16x32_bf16 v[118:121], v[178:181], v[146:149], v[118:121]
	v_mfma_f32_16x16x32_bf16 v[114:117], v[200:203], v[146:149], v[114:117]
	v_mfma_f32_16x16x32_bf16 v[102:105], v[178:181], v[154:157], v[102:105]
	v_mfma_f32_16x16x32_bf16 v[98:101], v[200:203], v[154:157], v[98:101]
	v_mfma_f32_16x16x32_bf16 v[86:89], v[178:181], v[162:165], v[86:89]
	v_mfma_f32_16x16x32_bf16 v[82:85], v[200:203], v[162:165], v[82:85]
	v_mfma_f32_16x16x32_bf16 v[70:73], v[178:181], v[170:173], v[70:73]
	v_mfma_f32_16x16x32_bf16 v[66:69], v[200:203], v[170:173], v[66:69]
	v_mfma_f32_16x16x32_bf16 v[118:121], v[182:185], v[150:153], v[118:121]
	v_mfma_f32_16x16x32_bf16 v[114:117], v[204:207], v[150:153], v[114:117]
	v_mfma_f32_16x16x32_bf16 v[102:105], v[182:185], v[158:161], v[102:105]
	v_mfma_f32_16x16x32_bf16 v[98:101], v[204:207], v[158:161], v[98:101]
	v_mfma_f32_16x16x32_bf16 v[86:89], v[182:185], v[166:169], v[86:89]
	v_mfma_f32_16x16x32_bf16 v[82:85], v[204:207], v[166:169], v[82:85]
	v_mfma_f32_16x16x32_bf16 v[70:73], v[182:185], v[174:177], v[70:73]
	v_mfma_f32_16x16x32_bf16 v[66:69], v[204:207], v[174:177], v[66:69]
	s_mov_b32 m0, s60
	s_barrier
	ds_read_b128 v[146:149], v213 offset:49152
	ds_read_b128 v[150:153], v213 offset:50176
	ds_read_b128 v[154:157], v213 offset:51200
	ds_read_b128 v[158:161], v213 offset:52224
	ds_read_b128 v[162:165], v213 offset:53248
	ds_read_b128 v[166:169], v213 offset:54272
	ds_read_b128 v[170:173], v213 offset:55296
	ds_read_b128 v[174:177], v213 offset:56320
	s_add_u32 s98, s100, s40
	s_addc_u32 s99, s101, s41
	global_load_lds_dwordx4 v190, s[98:99]
	s_mov_b32 m0, s61
	s_nop 0
	global_load_lds_dwordx4 v192, s[98:99]
	s_waitcnt vmcnt(10)
	s_barrier
	s_waitcnt lgkmcnt(0)
	v_mfma_f32_16x16x32_bf16 v[62:65], v[130:133], v[146:149], v[62:65]
	v_mfma_f32_16x16x32_bf16 v[58:61], v[138:141], v[146:149], v[58:61]
	v_mfma_f32_16x16x32_bf16 v[46:49], v[130:133], v[154:157], v[46:49]
	v_mfma_f32_16x16x32_bf16 v[42:45], v[138:141], v[154:157], v[42:45]
	v_mfma_f32_16x16x32_bf16 v[30:33], v[130:133], v[162:165], v[30:33]
	v_mfma_f32_16x16x32_bf16 v[26:29], v[138:141], v[162:165], v[26:29]
	v_mfma_f32_16x16x32_bf16 v[14:17], v[130:133], v[170:173], v[14:17]
	v_mfma_f32_16x16x32_bf16 v[10:13], v[138:141], v[170:173], v[10:13]
	v_mfma_f32_16x16x32_bf16 v[62:65], v[134:137], v[150:153], v[62:65]
	v_mfma_f32_16x16x32_bf16 v[58:61], v[142:145], v[150:153], v[58:61]
	v_mfma_f32_16x16x32_bf16 v[46:49], v[134:137], v[158:161], v[46:49]
	v_mfma_f32_16x16x32_bf16 v[42:45], v[142:145], v[158:161], v[42:45]
	v_mfma_f32_16x16x32_bf16 v[30:33], v[134:137], v[166:169], v[30:33]
	v_mfma_f32_16x16x32_bf16 v[26:29], v[142:145], v[166:169], v[26:29]
	v_mfma_f32_16x16x32_bf16 v[14:17], v[134:137], v[174:177], v[14:17]
	v_mfma_f32_16x16x32_bf16 v[10:13], v[142:145], v[174:177], v[10:13]
	s_barrier
	s_add_u32 s16, s86, 0xb0080
	s_addc_u32 s17, s87, 0
	s_add_i32 m0, s38, 0x1c000
	s_nop 0
	global_load_lds_dwordx4 v0, s[16:17]
	s_add_i32 m0, s38, 0x1e000
	s_nop 0
	global_load_lds_dwordx4 v194, s[16:17]
	ds_read_b128 v[130:133], v189
	ds_read_b128 v[134:137], v189 offset:1024
	ds_read_b128 v[138:141], v189 offset:2048
	ds_read_b128 v[142:145], v189 offset:3072
	s_waitcnt vmcnt(6)
	s_barrier
	v_mfma_f32_16x16x32_bf16 v[54:57], v[178:181], v[146:149], v[54:57]
	v_mfma_f32_16x16x32_bf16 v[50:53], v[200:203], v[146:149], v[50:53]
	v_mfma_f32_16x16x32_bf16 v[38:41], v[178:181], v[154:157], v[38:41]
	v_mfma_f32_16x16x32_bf16 v[34:37], v[200:203], v[154:157], v[34:37]
	v_mfma_f32_16x16x32_bf16 v[22:25], v[178:181], v[162:165], v[22:25]
	v_mfma_f32_16x16x32_bf16 v[18:21], v[200:203], v[162:165], v[18:21]
	v_mfma_f32_16x16x32_bf16 v[6:9], v[178:181], v[170:173], v[6:9]
	v_mfma_f32_16x16x32_bf16 v[2:5], v[200:203], v[170:173], v[2:5]
	v_mfma_f32_16x16x32_bf16 v[54:57], v[182:185], v[150:153], v[54:57]
	v_mfma_f32_16x16x32_bf16 v[50:53], v[204:207], v[150:153], v[50:53]
	v_mfma_f32_16x16x32_bf16 v[38:41], v[182:185], v[158:161], v[38:41]
	v_mfma_f32_16x16x32_bf16 v[34:37], v[204:207], v[158:161], v[34:37]
	v_mfma_f32_16x16x32_bf16 v[22:25], v[182:185], v[166:169], v[22:25]
	v_mfma_f32_16x16x32_bf16 v[18:21], v[204:207], v[166:169], v[18:21]
	v_mfma_f32_16x16x32_bf16 v[6:9], v[182:185], v[174:177], v[6:9]
	v_mfma_f32_16x16x32_bf16 v[2:5], v[204:207], v[174:177], v[2:5]
	s_add_i32 s79, s79, 2
	s_add_u32 s34, s34, 0x100
	s_addc_u32 s78, s78, 0
	s_mov_b64 s[16:17], s[84:85]
	s_add_u32 s84, s16, 0x100
	s_addc_u32 s85, s17, 0
	s_cmp_eq_u32 s79, 40
	s_cselect_b32 s89, s5, s85
	s_cselect_b32 s88, s4, s84
	s_cselect_b32 s87, s7, s78
	s_cselect_b32 s86, s6, s34
	s_cmp_gt_u32 s79, 41
	s_barrier
	s_cbranch_scc0 .LBB0_1090
	s_waitcnt lgkmcnt(0)
	s_lshl_b32 s16, s23, 8
	v_mov_b32_e32 v186, v252
	s_add_i32 s16, s16, s47
	s_nop 0
	v_and_or_b32 v202, v186, 15, s16
	s_lshl_b32 s16, s22, 8
	s_or_b32 s16, s16, s55
	v_lshrrev_b32_e32 v130, 1, v186
	v_and_or_b32 v200, v130, 24, s16
	v_ashrrev_i32_e32 v201, 31, v200
	v_ashrrev_i32_e32 v203, 31, v202
	v_lshl_add_u64 v[204:205], v[200:201], 2, s[12:13]
	v_lshlrev_b64 v[130:131], 12, v[202:203]
	v_lshl_add_u64 v[130:131], v[204:205], 0, v[130:131]
	global_load_dwordx4 v[216:219], v[130:131], off offset:16
	global_load_dwordx4 v[220:223], v[130:131], off
	global_load_dwordx4 v[178:181], v[130:131], off offset:528
	global_load_dwordx4 v[182:185], v[130:131], off offset:512
	v_or_b32_e32 v210, 16, v202
	v_ashrrev_i32_e32 v211, 31, v210
	v_lshlrev_b64 v[130:131], 12, v[210:211]
	v_or_b32_e32 v208, 32, v202
	v_lshl_add_u64 v[130:131], v[204:205], 0, v[130:131]
	v_ashrrev_i32_e32 v209, 31, v208
	global_load_dwordx4 v[170:173], v[130:131], off offset:16
	global_load_dwordx4 v[174:177], v[130:131], off
	global_load_dwordx4 v[162:165], v[130:131], off offset:528
	global_load_dwordx4 v[166:169], v[130:131], off offset:512
	v_lshlrev_b64 v[130:131], 12, v[208:209]
	v_or_b32_e32 v206, 48, v202
	v_lshl_add_u64 v[130:131], v[204:205], 0, v[130:131]
	v_ashrrev_i32_e32 v207, 31, v206
	global_load_dwordx4 v[154:157], v[130:131], off offset:16
	global_load_dwordx4 v[158:161], v[130:131], off
	global_load_dwordx4 v[138:141], v[130:131], off offset:528
	global_load_dwordx4 v[142:145], v[130:131], off offset:512
	v_lshlrev_b64 v[130:131], 12, v[206:207]
	v_lshl_add_u64 v[134:135], v[204:205], 0, v[130:131]
	global_load_dwordx4 v[146:149], v[134:135], off offset:16
	global_load_dwordx4 v[150:153], v[134:135], off
	global_load_dwordx4 v[130:133], v[134:135], off offset:528
	s_nop 0
	global_load_dwordx4 v[134:137], v[134:135], off offset:512
	v_and_b32_e32 v186, 63, v186
	v_lshlrev_b32_e32 v187, 2, v186
	v_xor_b32_e32 v215, 64, v187
	v_xor_b32_e32 v214, 0x80, v187
	v_cmp_gt_u32_e32 vcc, 16, v186
	v_lshlrev_b64 v[186:187], 10, v[202:203]
	v_lshl_add_u64 v[186:187], v[186:187], 0, v[200:201]
	s_lshl_b32 s16, s22, 2
	s_ashr_i32 s17, s16, 31
	s_waitcnt vmcnt(0)
	v_pk_add_f32 v[124:125], v[124:125], v[218:219]
	v_pk_add_f32 v[128:129], v[128:129], v[222:223]
	v_pk_add_f32 v[126:127], v[126:127], v[220:221]
	v_pk_mul_f32 v[218:219], v[128:129], v[128:129]
	v_pk_mul_f32 v[220:221], v[126:127], v[126:127]
	v_pk_add_f32 v[122:123], v[122:123], v[216:217]
	v_lshl_add_u64 v[216:217], v[186:187], 2, s[14:15]
	v_add_f32_e32 v220, v220, v221
	v_add_f32_e32 v218, v218, v219
	global_store_dwordx4 v[216:217], v[126:129], off
	global_store_dwordx4 v[216:217], v[122:125], off offset:16
	v_add_f32_e32 v222, v220, v218
	v_pk_mul_f32 v[220:221], v[122:123], v[122:123]
	v_cvt_pk_bf16_f32 v126, v126, v127
	v_cvt_pk_bf16_f32 v127, v128, v129
	v_cvt_pk_bf16_f32 v128, v122, v123
	v_cvt_pk_bf16_f32 v129, v124, v125
	v_lshl_add_u64 v[122:123], v[186:187], 1, s[80:81]
	v_pk_add_f32 v[120:121], v[120:121], v[184:185]
	v_pk_add_f32 v[118:119], v[118:119], v[182:183]
	v_pk_mul_f32 v[218:219], v[124:125], v[124:125]
	global_store_dwordx4 v[122:123], v[126:129], off
	v_pk_mul_f32 v[124:125], v[120:121], v[120:121]
	v_pk_add_f32 v[116:117], v[116:117], v[180:181]
	v_pk_mul_f32 v[126:127], v[118:119], v[118:119]
	v_pk_add_f32 v[114:115], v[114:115], v[178:179]
	v_add_f32_e32 v126, v126, v127
	v_add_f32_e32 v124, v124, v125
	v_add_f32_e32 v128, v126, v124
	v_pk_mul_f32 v[124:125], v[116:117], v[116:117]
	v_pk_mul_f32 v[126:127], v[114:115], v[114:115]
	v_add_f32_e32 v220, v220, v221
	v_add_f32_e32 v218, v218, v219
	v_add_f32_e32 v126, v126, v127
	v_add_f32_e32 v124, v124, v125
	v_add_f32_e32 v218, v220, v218
	v_add_f32_e32 v124, v126, v124
	v_add_f32_e32 v218, v222, v218
	v_add_f32_e32 v124, v128, v124
	v_add_f32_e32 v124, v218, v124
	global_store_dwordx4 v[216:217], v[118:121], off offset:512
	global_store_dwordx4 v[216:217], v[114:117], off offset:528
	s_nop 0
	v_cvt_pk_bf16_f32 v118, v118, v119
	v_cvt_pk_bf16_f32 v119, v120, v121
	v_cvt_pk_bf16_f32 v120, v114, v115
	ds_bpermute_b32 v114, v215, v124
	v_cvt_pk_bf16_f32 v121, v116, v117
	global_store_dwordx4 v[122:123], v[118:121], off offset:256
	s_waitcnt lgkmcnt(0)
	v_add_f32_e32 v114, v124, v114
	ds_bpermute_b32 v115, v214, v114
	s_and_saveexec_b64 s[22:23], vcc
	s_cbranch_execz .LBB0_1093
	v_lshlrev_b64 v[116:117], 6, v[202:203]
	v_lshl_add_u64 v[116:117], s[82:83], 0, v[116:117]
	v_lshl_add_u64 v[116:117], s[16:17], 2, v[116:117]
	s_lshl_b32 s34, s45, 2
	v_lshl_add_u64 v[116:117], v[116:117], 0, s[34:35]
	s_waitcnt lgkmcnt(0)
	v_add_f32_e32 v114, v114, v115
	global_store_dword v[116:117], v114, off
